# v040: v039 + SwiGLU epilogue: packed -log2e scale via VGPR constant, store addresses as 32-bit v_mad_u32_u24 offsets with SGPR base (saddr stores) instead of v_mad_i64_i32 + 64-bit adds
# speedup vs baseline: 1.0124x; 1.0070x over previous
; __device__ __forceinline__ unsigned cvt_pk_bf16(float lo, float hi) { unsigned r; asm volatile("v_cvt_pk_bf16_f32 %0, %1, %2" : "=v"(r) : "v"(lo), "v"(hi)); return r; }
;     __device__ __forceinline__ void operator()(const f32x4 (&acc)[2][2][4][2], const Unit& u, int wr, int wc, int fr, int fq) const {
;     ...
;         for (int ai = 0; ai < 2; ++ai)
; #pragma unroll
;             for (int m = 0; m < 4; ++m) {
;                 float g8[8], u8[8], v[8];
; #pragma unroll
;                 for (int n = 0; n < 2; ++n)
; #pragma unroll
;                     for (int j = 0; j < 4; ++j) { g8[4 * n + j] = acc[ai][0][m][n][j]; u8[4 * n + j] = acc[ai][1][m][n][j]; }
; #pragma unroll
;                 for (int e = 0; e < 8; ++e) v[e] = __builtin_amdgcn_exp2f(-1.4426950408889634f * g8[e]);
; #pragma unroll
;                 for (int e = 0; e < 8; ++e) v[e] = __builtin_amdgcn_rcpf(1.0f + v[e]);
; #pragma unroll
;                 for (int e = 0; e < 8; ++e) v[e] = (g8[e] * u8[e]) * v[e];
;                 u32x4e w; w.x = cvt_pk_bf16(v[0], v[1]); w.y = cvt_pk_bf16(v[2], v[3]); w.z = cvt_pk_bf16(v[4], v[5]); w.w = cvt_pk_bf16(v[6], v[7]);
;                 *(u32x4e*)(H + (size_t)(row0 + ai * HALF + m * 16) * ldc + col0) = w;
.LBB0_886:
	v_mov_b32_e32 v148, 0xbfb8aa3b
	v_pk_mul_f32 v[116:117], v[124:125], v[116:117]
	v_pk_mul_f32 v[118:119], v[126:127], v[118:119]
	v_pk_mul_f32 v[120:121], v[128:129], v[120:121]
	v_pk_mul_f32 v[122:123], v[130:131], v[122:123]
	v_pk_mul_f32 v[124:125], v[124:125], v[148:149] op_sel_hi:[1,0]
	v_pk_mul_f32 v[126:127], v[126:127], v[148:149] op_sel_hi:[1,0]
	v_pk_mul_f32 v[128:129], v[128:129], v[148:149] op_sel_hi:[1,0]
	v_pk_mul_f32 v[130:131], v[130:131], v[148:149] op_sel_hi:[1,0]
	v_exp_f32_e32 v124, v124
	v_exp_f32_e32 v125, v125
	v_exp_f32_e32 v126, v126
	v_exp_f32_e32 v127, v127
	v_exp_f32_e32 v128, v128
	v_exp_f32_e32 v129, v129
	v_exp_f32_e32 v130, v130
	v_exp_f32_e32 v131, v131
	s_nop 0
	v_pk_add_f32 v[124:125], v[124:125], 1.0 op_sel_hi:[1,0]
	v_pk_add_f32 v[126:127], v[126:127], 1.0 op_sel_hi:[1,0]
	v_pk_add_f32 v[128:129], v[128:129], 1.0 op_sel_hi:[1,0]
	v_pk_add_f32 v[130:131], v[130:131], 1.0 op_sel_hi:[1,0]
	v_rcp_f32_e32 v124, v124
	v_rcp_f32_e32 v125, v125
	v_rcp_f32_e32 v126, v126
	v_rcp_f32_e32 v127, v127
	v_rcp_f32_e32 v128, v128
	v_rcp_f32_e32 v129, v129
	v_rcp_f32_e32 v130, v130
	v_rcp_f32_e32 v131, v131
	s_nop 0
	v_pk_mul_f32 v[116:117], v[124:125], v[116:117]
	v_pk_mul_f32 v[118:119], v[126:127], v[118:119]
	v_pk_mul_f32 v[120:121], v[128:129], v[120:121]
	v_pk_mul_f32 v[122:123], v[130:131], v[122:123]
	v_lshl_or_b32 v144, s30, 7, v142
	v_lshl_add_u32 v146, s31, 8, v140
	v_ashrrev_i32_e32 v145, 31, v144
	v_cvt_pk_bf16_f32 v120, v120, v121
	v_cvt_pk_bf16_f32 v121, v122, v123
	v_cvt_pk_bf16_f32 v122, v116, v117
	v_mov_b64_e32 v[116:117], s[50:51]
	v_cvt_pk_bf16_f32 v123, v118, v119
	v_lshlrev_b64 v[118:119], 1, v[144:145]
	v_mad_u32_u24 v124, v146, s44, v118
	global_store_dwordx4 v124, v[120:123], s[50:51] sc1
	v_pk_mul_f32 v[100:101], v[108:109], v[100:101]
	v_pk_mul_f32 v[102:103], v[110:111], v[102:103]
	v_pk_mul_f32 v[104:105], v[112:113], v[104:105]
	v_pk_mul_f32 v[106:107], v[114:115], v[106:107]
	v_pk_mul_f32 v[108:109], v[108:109], v[148:149] op_sel_hi:[1,0]
	v_pk_mul_f32 v[110:111], v[110:111], v[148:149] op_sel_hi:[1,0]
	v_pk_mul_f32 v[112:113], v[112:113], v[148:149] op_sel_hi:[1,0]
	v_pk_mul_f32 v[114:115], v[114:115], v[148:149] op_sel_hi:[1,0]
	v_exp_f32_e32 v108, v108
	v_exp_f32_e32 v109, v109
	v_exp_f32_e32 v110, v110
	v_exp_f32_e32 v111, v111
	v_exp_f32_e32 v112, v112
	v_exp_f32_e32 v113, v113
	v_exp_f32_e32 v114, v114
	v_exp_f32_e32 v115, v115
	s_nop 0
	v_pk_add_f32 v[108:109], v[108:109], 1.0 op_sel_hi:[1,0]
	v_pk_add_f32 v[110:111], v[110:111], 1.0 op_sel_hi:[1,0]
	v_pk_add_f32 v[112:113], v[112:113], 1.0 op_sel_hi:[1,0]
	v_pk_add_f32 v[114:115], v[114:115], 1.0 op_sel_hi:[1,0]
	v_rcp_f32_e32 v108, v108
	v_rcp_f32_e32 v109, v109
	v_rcp_f32_e32 v110, v110
	v_rcp_f32_e32 v111, v111
	v_rcp_f32_e32 v112, v112
	v_rcp_f32_e32 v113, v113
	v_rcp_f32_e32 v114, v114
	v_rcp_f32_e32 v115, v115
	s_nop 0
	v_pk_mul_f32 v[108:109], v[108:109], v[100:101]
	v_mul_f32_e32 v110, v110, v102
	v_mul_f32_e32 v103, v111, v103
	v_pk_mul_f32 v[104:105], v[112:113], v[104:105]
	v_pk_mul_f32 v[106:107], v[114:115], v[106:107]
	v_cvt_pk_bf16_f32 v100, v104, v105
	v_or_b32_e32 v104, 16, v146
	v_mad_u32_u24 v104, v104, s44, v118
	v_cvt_pk_bf16_f32 v101, v106, v107
	v_cvt_pk_bf16_f32 v102, v108, v109
	v_cvt_pk_bf16_f32 v103, v110, v103
	global_store_dwordx4 v104, v[100:103], s[50:51] sc1
	v_pk_mul_f32 v[84:85], v[92:93], v[84:85]
	v_pk_mul_f32 v[86:87], v[94:95], v[86:87]
	v_pk_mul_f32 v[88:89], v[96:97], v[88:89]
	v_pk_mul_f32 v[90:91], v[98:99], v[90:91]
	v_pk_mul_f32 v[92:93], v[92:93], v[148:149] op_sel_hi:[1,0]
	v_pk_mul_f32 v[94:95], v[94:95], v[148:149] op_sel_hi:[1,0]
	v_pk_mul_f32 v[96:97], v[96:97], v[148:149] op_sel_hi:[1,0]
	v_pk_mul_f32 v[98:99], v[98:99], v[148:149] op_sel_hi:[1,0]
	v_exp_f32_e32 v92, v92
	v_exp_f32_e32 v93, v93
	v_exp_f32_e32 v94, v94
	v_exp_f32_e32 v95, v95
	v_exp_f32_e32 v96, v96
	v_exp_f32_e32 v97, v97
	v_exp_f32_e32 v98, v98
	v_exp_f32_e32 v99, v99
	s_nop 0
	v_pk_add_f32 v[92:93], v[92:93], 1.0 op_sel_hi:[1,0]
	v_pk_add_f32 v[94:95], v[94:95], 1.0 op_sel_hi:[1,0]
	v_pk_add_f32 v[96:97], v[96:97], 1.0 op_sel_hi:[1,0]
	v_pk_add_f32 v[98:99], v[98:99], 1.0 op_sel_hi:[1,0]
	v_rcp_f32_e32 v92, v92
	v_rcp_f32_e32 v93, v93
	v_rcp_f32_e32 v94, v94
	v_rcp_f32_e32 v95, v95
	v_rcp_f32_e32 v96, v96
	v_rcp_f32_e32 v97, v97
	v_rcp_f32_e32 v98, v98
	v_rcp_f32_e32 v99, v99
	s_nop 0
	v_pk_mul_f32 v[92:93], v[92:93], v[84:85]
	v_mul_f32_e32 v94, v94, v86
	v_mul_f32_e32 v87, v95, v87
	v_pk_mul_f32 v[88:89], v[96:97], v[88:89]
	v_pk_mul_f32 v[90:91], v[98:99], v[90:91]
	v_cvt_pk_bf16_f32 v84, v88, v89
	v_or_b32_e32 v88, 32, v146
	v_mad_u32_u24 v88, v88, s44, v118
	v_cvt_pk_bf16_f32 v85, v90, v91
	v_cvt_pk_bf16_f32 v86, v92, v93
	v_cvt_pk_bf16_f32 v87, v94, v87
	global_store_dwordx4 v88, v[84:87], s[50:51] sc1
	v_pk_mul_f32 v[68:69], v[76:77], v[68:69]
	v_pk_mul_f32 v[70:71], v[78:79], v[70:71]
	v_pk_mul_f32 v[72:73], v[80:81], v[72:73]
	v_pk_mul_f32 v[74:75], v[82:83], v[74:75]
	v_pk_mul_f32 v[76:77], v[76:77], v[148:149] op_sel_hi:[1,0]
	v_pk_mul_f32 v[78:79], v[78:79], v[148:149] op_sel_hi:[1,0]
	v_pk_mul_f32 v[80:81], v[80:81], v[148:149] op_sel_hi:[1,0]
	v_pk_mul_f32 v[82:83], v[82:83], v[148:149] op_sel_hi:[1,0]
	v_exp_f32_e32 v76, v76
	v_exp_f32_e32 v77, v77
	v_exp_f32_e32 v78, v78
	v_exp_f32_e32 v79, v79
	v_exp_f32_e32 v80, v80
	v_exp_f32_e32 v81, v81
	v_exp_f32_e32 v82, v82
	v_exp_f32_e32 v83, v83
	s_nop 0
	v_pk_add_f32 v[76:77], v[76:77], 1.0 op_sel_hi:[1,0]
	v_pk_add_f32 v[78:79], v[78:79], 1.0 op_sel_hi:[1,0]
	v_pk_add_f32 v[80:81], v[80:81], 1.0 op_sel_hi:[1,0]
; __device__ __forceinline__ unsigned cvt_pk_bf16(float lo, float hi) { unsigned r; asm volatile("v_cvt_pk_bf16_f32 %0, %1, %2" : "=v"(r) : "v"(lo), "v"(hi)); return r; }
;     __device__ __forceinline__ void operator()(const f32x4 (&acc)[2][2][4][2], const Unit& u, int wr, int wc, int fr, int fq) const {
;     ...
;         for (int ai = 0; ai < 2; ++ai)
; #pragma unroll
;             for (int m = 0; m < 4; ++m) {
;                 float g8[8], u8[8], v[8];
; #pragma unroll
;                 for (int n = 0; n < 2; ++n)
; #pragma unroll
;                     for (int j = 0; j < 4; ++j) { g8[4 * n + j] = acc[ai][0][m][n][j]; u8[4 * n + j] = acc[ai][1][m][n][j]; }
; #pragma unroll
;                 for (int e = 0; e < 8; ++e) v[e] = __builtin_amdgcn_exp2f(-1.4426950408889634f * g8[e]);
; #pragma unroll
;                 for (int e = 0; e < 8; ++e) v[e] = __builtin_amdgcn_rcpf(1.0f + v[e]);
; #pragma unroll
;                 for (int e = 0; e < 8; ++e) v[e] = (g8[e] * u8[e]) * v[e];
;                 u32x4e w; w.x = cvt_pk_bf16(v[0], v[1]); w.y = cvt_pk_bf16(v[2], v[3]); w.z = cvt_pk_bf16(v[4], v[5]); w.w = cvt_pk_bf16(v[6], v[7]);
;                 *(u32x4e*)(H + (size_t)(row0 + ai * HALF + m * 16) * ldc + col0) = w;
	v_pk_add_f32 v[82:83], v[82:83], 1.0 op_sel_hi:[1,0]
	v_rcp_f32_e32 v76, v76
	v_rcp_f32_e32 v77, v77
	v_rcp_f32_e32 v78, v78
	v_rcp_f32_e32 v79, v79
	v_rcp_f32_e32 v80, v80
	v_rcp_f32_e32 v81, v81
	v_rcp_f32_e32 v82, v82
	v_rcp_f32_e32 v83, v83
	s_nop 0
	v_pk_mul_f32 v[76:77], v[76:77], v[68:69]
	v_mul_f32_e32 v78, v78, v70
	v_mul_f32_e32 v71, v79, v71
	v_pk_mul_f32 v[72:73], v[80:81], v[72:73]
	v_pk_mul_f32 v[74:75], v[82:83], v[74:75]
	v_cvt_pk_bf16_f32 v68, v72, v73
	v_or_b32_e32 v72, 48, v146
	v_mad_u32_u24 v72, v72, s44, v118
	v_cvt_pk_bf16_f32 v69, v74, v75
	v_cvt_pk_bf16_f32 v70, v76, v77
	v_cvt_pk_bf16_f32 v71, v78, v71
	global_store_dwordx4 v72, v[68:71], s[50:51] sc1
	v_pk_mul_f32 v[52:53], v[60:61], v[52:53]
	v_pk_mul_f32 v[54:55], v[62:63], v[54:55]
	v_pk_mul_f32 v[56:57], v[64:65], v[56:57]
	v_pk_mul_f32 v[58:59], v[66:67], v[58:59]
	v_pk_mul_f32 v[60:61], v[60:61], v[148:149] op_sel_hi:[1,0]
	v_pk_mul_f32 v[62:63], v[62:63], v[148:149] op_sel_hi:[1,0]
	v_pk_mul_f32 v[64:65], v[64:65], v[148:149] op_sel_hi:[1,0]
	v_pk_mul_f32 v[66:67], v[66:67], v[148:149] op_sel_hi:[1,0]
	v_exp_f32_e32 v60, v60
	v_exp_f32_e32 v61, v61
	v_exp_f32_e32 v62, v62
	v_exp_f32_e32 v63, v63
	v_exp_f32_e32 v64, v64
	v_exp_f32_e32 v65, v65
	v_exp_f32_e32 v66, v66
	v_exp_f32_e32 v67, v67
	s_nop 0
	v_pk_add_f32 v[60:61], v[60:61], 1.0 op_sel_hi:[1,0]
	v_pk_add_f32 v[62:63], v[62:63], 1.0 op_sel_hi:[1,0]
	v_pk_add_f32 v[64:65], v[64:65], 1.0 op_sel_hi:[1,0]
	v_pk_add_f32 v[66:67], v[66:67], 1.0 op_sel_hi:[1,0]
	v_rcp_f32_e32 v60, v60
	v_rcp_f32_e32 v61, v61
	v_rcp_f32_e32 v62, v62
	v_rcp_f32_e32 v63, v63
	v_rcp_f32_e32 v64, v64
	v_rcp_f32_e32 v65, v65
	v_rcp_f32_e32 v66, v66
	v_rcp_f32_e32 v67, v67
	s_nop 0
	v_pk_mul_f32 v[60:61], v[60:61], v[52:53]
	v_mul_f32_e32 v62, v62, v54
	v_mul_f32_e32 v55, v63, v55
	v_pk_mul_f32 v[56:57], v[64:65], v[56:57]
	v_pk_mul_f32 v[58:59], v[66:67], v[58:59]
	v_add_u32_e32 v68, 0x80, v146
	v_cvt_pk_bf16_f32 v52, v56, v57
	v_mad_u32_u24 v56, v68, s44, v118
	v_cvt_pk_bf16_f32 v53, v58, v59
	v_cvt_pk_bf16_f32 v54, v60, v61
	v_cvt_pk_bf16_f32 v55, v62, v55
	global_store_dwordx4 v56, v[52:55], s[50:51] sc1
	v_pk_mul_f32 v[36:37], v[44:45], v[36:37]
	v_pk_mul_f32 v[38:39], v[46:47], v[38:39]
	v_pk_mul_f32 v[40:41], v[48:49], v[40:41]
	v_pk_mul_f32 v[42:43], v[50:51], v[42:43]
	v_pk_mul_f32 v[44:45], v[44:45], v[148:149] op_sel_hi:[1,0]
	v_pk_mul_f32 v[46:47], v[46:47], v[148:149] op_sel_hi:[1,0]
	v_pk_mul_f32 v[48:49], v[48:49], v[148:149] op_sel_hi:[1,0]
	v_pk_mul_f32 v[50:51], v[50:51], v[148:149] op_sel_hi:[1,0]
	v_exp_f32_e32 v44, v44
	v_exp_f32_e32 v45, v45
	v_exp_f32_e32 v46, v46
	v_exp_f32_e32 v47, v47
	v_exp_f32_e32 v48, v48
	v_exp_f32_e32 v49, v49
	v_exp_f32_e32 v50, v50
	v_exp_f32_e32 v51, v51
	s_nop 0
	v_pk_add_f32 v[44:45], v[44:45], 1.0 op_sel_hi:[1,0]
	v_pk_add_f32 v[46:47], v[46:47], 1.0 op_sel_hi:[1,0]
	v_pk_add_f32 v[48:49], v[48:49], 1.0 op_sel_hi:[1,0]
	v_pk_add_f32 v[50:51], v[50:51], 1.0 op_sel_hi:[1,0]
	v_rcp_f32_e32 v44, v44
	v_rcp_f32_e32 v45, v45
	v_rcp_f32_e32 v46, v46
	v_rcp_f32_e32 v47, v47
	v_rcp_f32_e32 v48, v48
	v_rcp_f32_e32 v49, v49
	v_rcp_f32_e32 v50, v50
	v_rcp_f32_e32 v51, v51
	s_nop 0
	v_pk_mul_f32 v[44:45], v[44:45], v[36:37]
	v_mul_f32_e32 v46, v46, v38
	v_mul_f32_e32 v39, v47, v39
	v_pk_mul_f32 v[40:41], v[48:49], v[40:41]
	v_pk_mul_f32 v[42:43], v[50:51], v[42:43]
	v_cvt_pk_bf16_f32 v36, v40, v41
	v_add_u32_e32 v40, 0x90, v146
	v_mad_u32_u24 v40, v40, s44, v118
	v_cvt_pk_bf16_f32 v37, v42, v43
	v_cvt_pk_bf16_f32 v38, v44, v45
	v_cvt_pk_bf16_f32 v39, v46, v39
	global_store_dwordx4 v40, v[36:39], s[50:51] sc1
	v_pk_mul_f32 v[20:21], v[28:29], v[20:21]
	v_pk_mul_f32 v[22:23], v[30:31], v[22:23]
	v_pk_mul_f32 v[24:25], v[32:33], v[24:25]
	v_pk_mul_f32 v[26:27], v[34:35], v[26:27]
	v_pk_mul_f32 v[28:29], v[28:29], v[148:149] op_sel_hi:[1,0]
	v_pk_mul_f32 v[30:31], v[30:31], v[148:149] op_sel_hi:[1,0]
	v_pk_mul_f32 v[32:33], v[32:33], v[148:149] op_sel_hi:[1,0]
	v_pk_mul_f32 v[34:35], v[34:35], v[148:149] op_sel_hi:[1,0]
	v_exp_f32_e32 v28, v28
	v_exp_f32_e32 v29, v29
	v_exp_f32_e32 v30, v30
	v_exp_f32_e32 v31, v31
	v_exp_f32_e32 v32, v32
	v_exp_f32_e32 v33, v33
	v_exp_f32_e32 v34, v34
	v_exp_f32_e32 v35, v35
	s_nop 0
	v_pk_add_f32 v[28:29], v[28:29], 1.0 op_sel_hi:[1,0]
	v_pk_add_f32 v[30:31], v[30:31], 1.0 op_sel_hi:[1,0]
	v_pk_add_f32 v[32:33], v[32:33], 1.0 op_sel_hi:[1,0]
	v_pk_add_f32 v[34:35], v[34:35], 1.0 op_sel_hi:[1,0]
	v_rcp_f32_e32 v28, v28
	v_rcp_f32_e32 v29, v29
	v_rcp_f32_e32 v30, v30
	v_rcp_f32_e32 v31, v31
	v_rcp_f32_e32 v32, v32
	v_rcp_f32_e32 v33, v33
	v_rcp_f32_e32 v34, v34
	v_rcp_f32_e32 v35, v35
	s_nop 0
	v_pk_mul_f32 v[28:29], v[28:29], v[20:21]
	v_mul_f32_e32 v30, v30, v22
	v_mul_f32_e32 v23, v31, v23
	v_pk_mul_f32 v[24:25], v[32:33], v[24:25]
	v_pk_mul_f32 v[26:27], v[34:35], v[26:27]
	v_cvt_pk_bf16_f32 v20, v24, v25
	v_add_u32_e32 v24, 0xa0, v146
	v_mad_u32_u24 v24, v24, s44, v118
	v_cvt_pk_bf16_f32 v21, v26, v27
	v_cvt_pk_bf16_f32 v22, v28, v29
	v_cvt_pk_bf16_f32 v23, v30, v23
	global_store_dwordx4 v24, v[20:23], s[50:51] sc1
	v_pk_mul_f32 v[4:5], v[12:13], v[4:5]
	v_pk_mul_f32 v[6:7], v[14:15], v[6:7]
	v_pk_mul_f32 v[8:9], v[16:17], v[8:9]
	v_pk_mul_f32 v[10:11], v[18:19], v[10:11]
	v_pk_mul_f32 v[12:13], v[12:13], v[148:149] op_sel_hi:[1,0]
	v_pk_mul_f32 v[14:15], v[14:15], v[148:149] op_sel_hi:[1,0]
	v_pk_mul_f32 v[16:17], v[16:17], v[148:149] op_sel_hi:[1,0]
	v_pk_mul_f32 v[18:19], v[18:19], v[148:149] op_sel_hi:[1,0]
	v_exp_f32_e32 v12, v12
	v_exp_f32_e32 v13, v13
	v_exp_f32_e32 v14, v14
	v_exp_f32_e32 v15, v15
	v_exp_f32_e32 v16, v16
	v_exp_f32_e32 v17, v17
	v_exp_f32_e32 v18, v18
	v_exp_f32_e32 v19, v19
	s_nop 0
	v_pk_add_f32 v[12:13], v[12:13], 1.0 op_sel_hi:[1,0]
	v_pk_add_f32 v[14:15], v[14:15], 1.0 op_sel_hi:[1,0]
	v_pk_add_f32 v[16:17], v[16:17], 1.0 op_sel_hi:[1,0]
	v_pk_add_f32 v[18:19], v[18:19], 1.0 op_sel_hi:[1,0]
	v_rcp_f32_e32 v12, v12
	v_rcp_f32_e32 v13, v13
	v_rcp_f32_e32 v14, v14
	v_rcp_f32_e32 v15, v15
	v_rcp_f32_e32 v16, v16
	v_rcp_f32_e32 v17, v17
	v_rcp_f32_e32 v18, v18
	v_rcp_f32_e32 v19, v19
	s_nop 0
	v_pk_mul_f32 v[12:13], v[12:13], v[4:5]
	v_mul_f32_e32 v14, v14, v6
	v_mul_f32_e32 v7, v15, v7
	v_pk_mul_f32 v[8:9], v[16:17], v[8:9]
	v_pk_mul_f32 v[10:11], v[18:19], v[10:11]
	v_cvt_pk_bf16_f32 v4, v8, v9
	v_add_u32_e32 v8, 0xb0, v146
	v_mad_u32_u24 v8, v8, s44, v118
	s_andn2_b64 vcc, exec, s[0:1]
	s_mov_b64 s[0:1], -1
	v_cvt_pk_bf16_f32 v5, v10, v11
	v_cvt_pk_bf16_f32 v6, v12, v13
	v_cvt_pk_bf16_f32 v7, v14, v7
	global_store_dwordx4 v8, v[4:7], s[50:51] sc1
	s_cbranch_vccnz .LBB0_879
	s_andn2_b64 vcc, exec, s[4:5]
	s_cbranch_vccnz .LBB0_878
	s_barrier
	s_branch .LBB0_878
